# GEMM main loop: static s_setprio 1 for waves 0-3 instead of 4-7 (per-half A/B of lever 4), per-segment flips removed, on top of v86
# speedup vs baseline: 1.0011x; 1.0011x over previous
.LBB0_2001:
	s_add_u32 s11, s24, 0x100
	s_addc_u32 s71, s25, 0
	s_add_u32 s2, s72, 0x80
	v_mov_b32_e32 v2, 0
	s_addc_u32 s3, s73, 0
	v_mov_b32_e32 v3, v2
	v_mov_b32_e32 v4, v2
	v_mov_b32_e32 v5, v2
	v_mov_b32_e32 v6, v2
	v_mov_b32_e32 v7, v2
	v_mov_b32_e32 v8, v2
	v_mov_b32_e32 v9, v2
	v_mov_b32_e32 v18, v2
	v_mov_b32_e32 v19, v2
	v_mov_b32_e32 v20, v2
	v_mov_b32_e32 v21, v2
	v_mov_b32_e32 v22, v2
	v_mov_b32_e32 v23, v2
	v_mov_b32_e32 v24, v2
	v_mov_b32_e32 v25, v2
	v_mov_b32_e32 v34, v2
	v_mov_b32_e32 v35, v2
	v_mov_b32_e32 v36, v2
	v_mov_b32_e32 v37, v2
	v_mov_b32_e32 v46, v2
	v_mov_b32_e32 v47, v2
	v_mov_b32_e32 v48, v2
	v_mov_b32_e32 v49, v2
	v_mov_b32_e32 v58, v2
	v_mov_b32_e32 v59, v2
	v_mov_b32_e32 v60, v2
	v_mov_b32_e32 v61, v2
	v_mov_b32_e32 v62, v2
	v_mov_b32_e32 v63, v2
	v_mov_b32_e32 v64, v2
	v_mov_b32_e32 v65, v2
	v_mov_b32_e32 v10, v2
	v_mov_b32_e32 v11, v2
	v_mov_b32_e32 v12, v2
	v_mov_b32_e32 v13, v2
	v_mov_b32_e32 v14, v2
	v_mov_b32_e32 v15, v2
	v_mov_b32_e32 v16, v2
	v_mov_b32_e32 v17, v2
	v_mov_b32_e32 v26, v2
	v_mov_b32_e32 v27, v2
	v_mov_b32_e32 v28, v2
	v_mov_b32_e32 v29, v2
	v_mov_b32_e32 v30, v2
	v_mov_b32_e32 v31, v2
	v_mov_b32_e32 v32, v2
	v_mov_b32_e32 v33, v2
	v_mov_b32_e32 v38, v2
	v_mov_b32_e32 v39, v2
	v_mov_b32_e32 v40, v2
	v_mov_b32_e32 v41, v2
	v_mov_b32_e32 v42, v2
	v_mov_b32_e32 v43, v2
	v_mov_b32_e32 v44, v2
	v_mov_b32_e32 v45, v2
	v_mov_b32_e32 v50, v2
	v_mov_b32_e32 v51, v2
	v_mov_b32_e32 v52, v2
	v_mov_b32_e32 v53, v2
	v_mov_b32_e32 v54, v2
	v_mov_b32_e32 v55, v2
	v_mov_b32_e32 v56, v2
	v_mov_b32_e32 v57, v2
	v_mov_b32_e32 v74, v2
	v_mov_b32_e32 v75, v2
	v_mov_b32_e32 v76, v2
	v_mov_b32_e32 v77, v2
	v_mov_b32_e32 v78, v2
	v_mov_b32_e32 v79, v2
	v_mov_b32_e32 v80, v2
	v_mov_b32_e32 v81, v2
	v_mov_b32_e32 v90, v2
	v_mov_b32_e32 v91, v2
	v_mov_b32_e32 v92, v2
	v_mov_b32_e32 v93, v2
	v_mov_b32_e32 v94, v2
	v_mov_b32_e32 v95, v2
	v_mov_b32_e32 v96, v2
	v_mov_b32_e32 v97, v2
	v_mov_b32_e32 v106, v2
	v_mov_b32_e32 v107, v2
	v_mov_b32_e32 v108, v2
	v_mov_b32_e32 v109, v2
	v_mov_b32_e32 v110, v2
	v_mov_b32_e32 v111, v2
	v_mov_b32_e32 v112, v2
	v_mov_b32_e32 v113, v2
	v_mov_b32_e32 v126, v2
	v_mov_b32_e32 v127, v2
	v_mov_b32_e32 v128, v2
	v_mov_b32_e32 v129, v2
	v_mov_b32_e32 v114, v2
	v_mov_b32_e32 v115, v2
	v_mov_b32_e32 v116, v2
	v_mov_b32_e32 v117, v2
	v_mov_b32_e32 v66, v2
	v_mov_b32_e32 v67, v2
	v_mov_b32_e32 v68, v2
	v_mov_b32_e32 v69, v2
	v_mov_b32_e32 v70, v2
	v_mov_b32_e32 v71, v2
	v_mov_b32_e32 v72, v2
	v_mov_b32_e32 v73, v2
	v_mov_b32_e32 v82, v2
	v_mov_b32_e32 v83, v2
	v_mov_b32_e32 v84, v2
	v_mov_b32_e32 v85, v2
	v_mov_b32_e32 v86, v2
	v_mov_b32_e32 v87, v2
	v_mov_b32_e32 v88, v2
	v_mov_b32_e32 v89, v2
	v_mov_b32_e32 v98, v2
	v_mov_b32_e32 v99, v2
	v_mov_b32_e32 v100, v2
	v_mov_b32_e32 v101, v2
	v_mov_b32_e32 v102, v2
	v_mov_b32_e32 v103, v2
	v_mov_b32_e32 v104, v2
	v_mov_b32_e32 v105, v2
	v_mov_b32_e32 v118, v2
	v_mov_b32_e32 v119, v2
	v_mov_b32_e32 v120, v2
	v_mov_b32_e32 v121, v2
	v_mov_b32_e32 v122, v2
	v_mov_b32_e32 v123, v2
	v_mov_b32_e32 v124, v2
	v_mov_b32_e32 v125, v2
	v_readlane_b32 s72, v251, 0
	s_cmp_lt_u32 s72, 4
	s_cbranch_scc0 .Lgp_older
	s_setprio 1
